# prologue: modulation partial-sum chains issue all loads before summing (same order); table work moved to workgroups with fewer GEMV items
# speedup vs baseline: 1.0090x; 1.0029x over previous
; __device__ __forceinline__ void p0a(Frame& F, const Args& AR) {
;     ...
;     const int gw = F.bid * NWAVES + F.wave, NGW = F.G * NWAVES;
;     const int gt = F.bid * NTHR + F.tid, NGT = F.G * NTHR;
;     {
;         float* rope = (float*)(ws + WS_ROPE);
;         for (int i = gt; i < 64 * 16; i += NGT) { const int pos = i >> 4, j = i & 15;
;             const double inv = exp(-(double)j * (9.210340371976184 / 16.0)); const double t = (double)pos * inv * 0.15915494309189535; const double fr = t - rint(t);
;             rope[2 * i] = (float)cospi(2.0 * fr); rope[2 * i + 1] = (float)sinpi(2.0 * fr); }
.LBB0_5:
	s_or_b64 exec, exec, s[0:1]
	v_writelane_b32 v250, s56, 34
	s_cmp_lt_i32 s82, 1
	s_cselect_b64 s[0:1], -1, 0
	v_writelane_b32 v250, s57, 35
	v_writelane_b32 v250, s58, 36
	v_writelane_b32 v250, s59, 37
	v_writelane_b32 v250, s60, 38
	v_writelane_b32 v250, s61, 39
	v_writelane_b32 v250, s62, 40
	v_writelane_b32 v250, s63, 41
	v_writelane_b32 v250, s64, 42
	v_writelane_b32 v250, s65, 43
	v_writelane_b32 v250, s66, 44
	v_writelane_b32 v250, s67, 45
	v_writelane_b32 v250, s68, 46
	v_writelane_b32 v250, s69, 47
	s_cmp_gt_i32 s83, 0
	v_writelane_b32 v250, s70, 48
	s_cselect_b64 s[4:5], -1, 0
	v_writelane_b32 v250, s71, 49
	s_and_b64 s[0:1], s[0:1], s[4:5]
	v_writelane_b32 v250, s92, 50
	s_andn2_b64 vcc, exec, s[0:1]
	s_nop 0
	v_writelane_b32 v250, s93, 51
	s_cbranch_vccnz .LBB0_200
	s_add_i32 s98, s80, 0x80
	s_and_b32 s98, s98, 0xff
	v_mov_b32_e32 v1, v0
	s_lshl_b32 s4, s33, 9
	v_readfirstlane_b32 s0, v1
	v_lshl_add_u32 v2, s98, 9, v1
	v_lshlrev_b32_e32 v3, 1, v1
	v_writelane_b32 v250, s0, 52
	s_movk_i32 s0, 0x400
	v_cmp_gt_i32_e32 vcc, s0, v2
	s_and_saveexec_b64 s[6:7], vcc
	s_cbranch_execz .LBB0_9
	v_and_b32_e32 v4, 15, v1
	s_mov_b32 s0, 0xbbb55516
	v_cvt_f64_u32_e32 v[4:5], v4
	s_mov_b32 s1, 0xbfe26bb1
	v_mul_f64 v[4:5], v[4:5], s[0:1]
	s_mov_b32 s0, 0x652b82fe
	s_mov_b32 s1, 0x3ff71547
	v_mul_f64 v[6:7], v[4:5], s[0:1]
	s_mov_b32 s0, 0xfefa39ef
	v_rndne_f64_e32 v[6:7], v[6:7]
	s_mov_b32 s1, 0xbfe62e42
	v_fma_f64 v[8:9], s[0:1], v[6:7], v[4:5]
	s_mov_b32 s0, 0x3b39803f
	s_mov_b32 s1, 0xbc7abc9e
	v_fmac_f64_e32 v[8:9], s[0:1], v[6:7]
	s_mov_b32 s0, 0x6a5dcb37
	v_mov_b32_e32 v10, 0xfca7ab0c
	v_mov_b32_e32 v11, 0x3e928af3
	s_mov_b32 s1, 0x3e5ade15
	v_fmac_f64_e32 v[10:11], s[0:1], v[8:9]
	v_mov_b32_e32 v12, 0x623fde64
	v_mov_b32_e32 v13, 0x3ec71dee
	v_fmac_f64_e32 v[12:13], v[8:9], v[10:11]
	v_mov_b32_e32 v10, 0x7c89e6b0
	v_mov_b32_e32 v11, 0x3efa0199
	v_fmac_f64_e32 v[10:11], v[8:9], v[12:13]
	v_mov_b32_e32 v12, 0x14761f6e
	v_mov_b32_e32 v13, 0x3f2a01a0
	v_fmac_f64_e32 v[12:13], v[8:9], v[10:11]
	v_mov_b32_e32 v10, 0x1852b7b0
	v_mov_b32_e32 v11, 0x3f56c16c
	v_fmac_f64_e32 v[10:11], v[8:9], v[12:13]
	v_mov_b32_e32 v12, 0x11122322
	v_mov_b32_e32 v13, 0x3f811111
	v_fmac_f64_e32 v[12:13], v[8:9], v[10:11]
	v_mov_b32_e32 v10, 0x555502a1
	v_mov_b32_e32 v11, 0x3fa55555
	v_fmac_f64_e32 v[10:11], v[8:9], v[12:13]
	v_mov_b32_e32 v12, 0x55555511
	v_mov_b32_e32 v13, 0x3fc55555
	v_fmac_f64_e32 v[12:13], v[8:9], v[10:11]
	v_mov_b32_e32 v10, 11
	v_mov_b32_e32 v11, 0x3fe00000
	s_mov_b32 s0, 0
	v_fmac_f64_e32 v[10:11], v[8:9], v[12:13]
	s_mov_b32 s1, 0x40900000
	v_fma_f64 v[10:11], v[8:9], v[10:11], 1.0
	v_cmp_nlt_f64_e32 vcc, s[0:1], v[4:5]
	s_mov_b32 s0, 0
	v_fma_f64 v[8:9], v[8:9], v[10:11], 1.0
	v_cvt_i32_f64_e32 v6, v[6:7]
	s_mov_b32 s1, 0xc090cc00
	s_add_u32 s8, s90, 0x200000
	v_ldexp_f64 v[6:7], v[8:9], v6
	v_mov_b32_e32 v8, 0x7ff00000
	v_cmp_ngt_f64_e64 s[0:1], s[0:1], v[4:5]
	s_addc_u32 s9, s91, 0
	v_cndmask_b32_e32 v7, v8, v7, vcc
	s_and_b64 vcc, s[0:1], vcc
	s_mov_b32 s10, 0x6dc9c883
	s_mov_b32 s12, 0
	s_mov_b32 s14, 0xf99eb0bb
	s_mov_b32 s16, 0x54442d18
	s_mov_b32 s18, 0x2e21c33
	v_cndmask_b32_e64 v5, 0, v7, s[0:1]
	v_cndmask_b32_e32 v4, 0, v6, vcc
	v_lshl_add_u32 v6, s98, 10, v3
	s_lshl_b32 s5, s33, 10
	s_mov_b64 s[0:1], 0
	s_mov_b32 s11, 0x3fc45f30
	s_mov_b32 s13, 0x7ff00000
	v_mov_b32_e32 v8, 0x6fdffd2b
	v_mov_b32_e32 v9, 0xbf7e2fe7
	s_mov_b32 s15, 0x3f3e357e
	v_mov_b32_e32 v10, 0xd5f14825
	v_mov_b32_e32 v11, 0x3fb50782
	v_mov_b32_e32 v12, 0xcdfe9424
	v_mov_b32_e32 v13, 0xbfe32d2c
	v_mov_b32_e32 v14, 0x67754fff
	v_mov_b32_e32 v15, 0x400466bc
	v_mov_b32_e32 v16, 0xe625be09
	v_mov_b32_e32 v17, 0xc014abbc
	s_mov_b32 s17, 0x400921fb
	v_mov_b32_e32 v18, 0xca1d4f33
	v_mov_b32_e32 v19, 0x3f5f9c89
	s_mov_b32 s19, 0xbf1b1673
	v_mov_b32_e32 v20, 0x7294bff9
	v_mov_b32_e32 v21, 0xbf9a6d1e
	v_mov_b32_e32 v22, 0x67b90b37
	v_mov_b32_e32 v23, 0x3fce1f50
	v_mov_b32_e32 v24, 0x7e3c325b
	v_mov_b32_e32 v25, 0xbff55d3c
	v_mov_b32_e32 v26, 0x81b5a67
	v_mov_b32_e32 v27, 0x40103c1f
	v_mov_b32_e32 v28, 0xc9be45de
	v_mov_b32_e32 v29, 0xc013bd3c
	s_brev_b32 s20, 1
	s_movk_i32 s21, 0x1f8
	v_mov_b32_e32 v30, 0x7ff80000
	s_movk_i32 s22, 0x3ff
	v_mov_b32_e32 v31, v2

; __device__ __forceinline__ void p0a(Frame& F, const Args& AR) {
;     ...
;         float* tw = (float*)(ws + WS_TW);
;         for (int i = gt; i < 4096; i += NGT) { const double fr = (double)i / 4096.0; tw[2 * i] = (float)cospi(2.0 * fr); tw[2 * i + 1] = (float)(-sinpi(2.0 * fr)); }
.LBB0_9:
	s_or_b64 exec, exec, s[6:7]
	s_movk_i32 s0, 0x1000
	v_cmp_gt_i32_e32 vcc, s0, v2
	s_and_saveexec_b64 s[0:1], vcc
	s_cbranch_execz .LBB0_12
	s_add_u32 s6, s90, 0x210000
	s_mov_b32 s10, 0
	s_mov_b32 s12, 0xf99eb0bb
	s_mov_b32 s14, 0x54442d18
	s_mov_b32 s16, 0x2e21c33
	s_addc_u32 s7, s91, 0
	v_lshl_add_u32 v4, s98, 10, v3
	s_lshl_b32 s5, s33, 10
	s_mov_b64 s[8:9], 0
	s_mov_b32 s11, 0x7ff00000
	v_mov_b32_e32 v6, 0x6fdffd2b
	v_mov_b32_e32 v7, 0xbf7e2fe7
	s_mov_b32 s13, 0x3f3e357e
	v_mov_b32_e32 v8, 0xd5f14825
	v_mov_b32_e32 v9, 0x3fb50782
	v_mov_b32_e32 v10, 0xcdfe9424
	v_mov_b32_e32 v11, 0xbfe32d2c
	v_mov_b32_e32 v12, 0x67754fff
	v_mov_b32_e32 v13, 0x400466bc
	v_mov_b32_e32 v14, 0xe625be09
	v_mov_b32_e32 v15, 0xc014abbc
	s_mov_b32 s15, 0x400921fb
	v_mov_b32_e32 v16, 0xca1d4f33
	v_mov_b32_e32 v17, 0x3f5f9c89
	s_mov_b32 s17, 0xbf1b1673
	v_mov_b32_e32 v18, 0x7294bff9
	v_mov_b32_e32 v19, 0xbf9a6d1e
	v_mov_b32_e32 v20, 0x67b90b37
	v_mov_b32_e32 v21, 0x3fce1f50
	v_mov_b32_e32 v22, 0x7e3c325b
	v_mov_b32_e32 v23, 0xbff55d3c
	v_mov_b32_e32 v24, 0x81b5a67
	v_mov_b32_e32 v25, 0x40103c1f
	v_mov_b32_e32 v26, 0xc9be45de
	v_mov_b32_e32 v27, 0xc013bd3c
	s_brev_b32 s18, 1
	s_movk_i32 s19, 0x1f8
	v_mov_b32_e32 v3, 0x7ff80000
	s_movk_i32 s20, 0xfff
	v_mov_b32_e32 v28, v2

; __device__ __forceinline__ void p0a(Frame& F, const Args& AR) {
;     ...
;         float* sct = (float*)(ws + WS_SSMCT);
;         for (int i = gt; i < DEPTH * 2 * 64 * 512; i += NGT) { const int ch = i & 511, p = (i >> 9) & 63, ld = i >> 15;
;             const size_t src = ((size_t)ld * 512 + ch) * 64 + p; sct[2 * (size_t)i] = AR.in[I_CRE][src]; sct[2 * (size_t)i + 1] = AR.in[I_CIM][src]; }
.LBB0_17:
	v_readlane_b32 s0, v250, 54
	v_readlane_b32 s1, v250, 55
	s_or_b64 exec, exec, s[0:1]
	s_mov_b32 s0, 0x40000
	v_cmp_gt_i32_e32 vcc, s0, v2
	s_and_saveexec_b64 s[0:1], vcc
	v_readlane_b32 s56, v250, 34
	v_readlane_b32 s58, v250, 36
	v_readlane_b32 s59, v250, 37
	v_readlane_b32 s60, v250, 38
	v_readlane_b32 s61, v250, 39
	v_readlane_b32 s62, v250, 40
	v_readlane_b32 s63, v250, 41
	v_readlane_b32 s64, v250, 42
	v_readlane_b32 s65, v250, 43
	v_readlane_b32 s57, v250, 35
	v_readlane_b32 s66, v250, 44
	v_readlane_b32 s67, v250, 45
	v_readlane_b32 s68, v250, 46
	v_readlane_b32 s69, v250, 47
	v_readlane_b32 s70, v250, 48
	v_readlane_b32 s71, v250, 49
	s_cbranch_execz .LBB0_20
	v_ashrrev_i32_e32 v3, 31, v2
	v_lshl_add_u64 v[4:5], v[2:3], 3, s[90:91]
	s_mov_b64 s[6:7], 0x500000
	s_ashr_i32 s5, s4, 31
	v_lshlrev_b32_e32 v3, 6, v1
	v_lshl_add_u64 v[4:5], v[4:5], 0, s[6:7]
	s_lshl_b64 s[6:7], s[4:5], 3
	v_lshl_add_u32 v3, s98, 15, v3
	s_lshl_b32 s5, s33, 15
	s_mov_b64 s[8:9], 0
	s_mov_b32 s10, 0x3ffff

; __device__ __forceinline__ void p0b(Frame& F, const Args& AR) {
;     ...
;         auto modval = [&](int l, int v, int j) { float s = AR.in[I_BMOD][l * MODW + j]; const float* q = modp + (size_t)(l * 3 + v) * MODW + j;
;             for (int ch = 0; ch < MOD_CHUNKS; ++ch) s += q[(size_t)ch * DEPTH * 3 * MODW]; return s; };
;         for (int e = gt; e < 13 * 3 * DM; e += NGT) { const int c = e % DM, v = (e / DM) % 3, idx = e / (3 * DM);
;             float vg = 0.f, vs = 0.f, vh = 0.f;
;             if (idx == 12) { vs = ng[c] * (1.0f + modval(0, v, 1 * DM + c)); vh = modval(0, v, c); }
;             else { const int l = idx / 3, k = idx % 3;
;                 vg = (k == 1 ? 1.0f : 0.5f) * modval(l, v, (2 + 3 * k) * DM + c) * ng[(l * 6 + 1 + 2 * k) * DM + c];
.LBB0_204:
	v_ashrrev_i32_e32 v2, 31, v1
	v_lshrrev_b32_e32 v2, 21, v2
	v_add_u32_e32 v2, v1, v2
	v_ashrrev_i32_e32 v2, 11, v2
	v_mul_hi_i32 v5, v2, s21
	v_lshrrev_b32_e32 v6, 31, v5
	v_add_u32_e32 v5, v5, v6
	v_lshl_add_u32 v5, v5, 1, v5
	s_mov_b32 s0, 0x2aaaaaab
	v_mul_i32_i24_e32 v49, 0x800, v2
	v_sub_u32_e32 v11, v2, v5
	v_mul_hi_i32 v2, v1, s0
	v_lshrrev_b32_e32 v5, 31, v2
	v_ashrrev_i32_e32 v2, 10, v2
	v_sub_u32_e32 v4, v1, v49
	v_add_u32_e32 v14, v2, v5
	v_cmp_gt_i32_e32 vcc, s22, v1
	s_mov_b64 s[0:1], 0
	s_and_saveexec_b64 s[12:13], vcc
	s_xor_b64 s[12:13], exec, s[12:13]
	s_cbranch_execz .LBB0_213
	s_mov_b32 s0, 0x38e38e39
	v_mul_hi_i32 v2, v1, s0
	v_lshrrev_b32_e32 v5, 31, v2
	v_ashrrev_i32_e32 v2, 12, v2
	v_add_u32_e32 v50, v2, v5
	v_mul_hi_i32 v2, v14, s21
	v_lshrrev_b32_e32 v5, 31, v2
	v_add_u32_e32 v2, v2, v5
	v_lshl_add_u32 v2, v2, 1, v2
	v_sub_u32_e32 v2, v14, v2
	v_mul_i32_i24_e32 v5, 0x1800, v2
	v_sub_u32_e32 v5, v5, v49
	v_add_u32_e32 v47, v1, v5
	v_mul_i32_i24_e32 v5, 0x4800, v50
	s_movk_i32 s14, 0x1800
	v_mad_i32_i24 v5, v2, s14, v5
	v_sub_u32_e32 v5, v5, v49
	v_add_u32_e32 v48, v1, v5
	v_add_u32_e32 v8, 0x1000, v48
	v_readlane_b32 s56, v250, 2
	v_ashrrev_i32_e32 v9, 31, v8
	v_readlane_b32 s66, v250, 12
	v_readlane_b32 s67, v250, 13
	v_add_u32_e32 v6, 0x1000, v47
	v_mad_i32_i24 v5, v50, 3, v11
	v_lshl_add_u64 v[8:9], v[8:9], 2, s[66:67]
	global_load_dword v12, v[8:9], off
	v_mov_b64_e32 v[8:9], s[6:7]
	v_mad_i64_i32 v[8:9], s[14:15], v5, s22, v[8:9]
	v_ashrrev_i32_e32 v7, 31, v6
	v_lshl_add_u64 v[6:7], v[6:7], 2, v[8:9]
	v_add_co_u32_e32 v16, vcc, s23, v6
	global_load_dword v13, v[6:7], off
	s_nop 0
	v_addc_co_u32_e32 v17, vcc, 0, v7, vcc
	global_load_dword v15, v[16:17], off
	v_add_co_u32_e32 v16, vcc, s24, v6
	v_mul_i32_i24_e32 v5, 6, v50
	s_nop 0
	v_addc_co_u32_e32 v17, vcc, 0, v7, vcc
	v_add_co_u32_e32 v18, vcc, s25, v6
	global_load_dword v16, v[16:17], off
	s_nop 0
	v_addc_co_u32_e32 v19, vcc, 0, v7, vcc
	global_load_dword v17, v[18:19], off
	v_add_co_u32_e32 v18, vcc, s26, v6
	v_lshlrev_b32_e32 v5, 11, v5
	s_nop 0
	v_addc_co_u32_e32 v19, vcc, 0, v7, vcc
	v_add_co_u32_e32 v20, vcc, s27, v6
	global_load_dword v18, v[18:19], off
	s_nop 0
	v_addc_co_u32_e32 v21, vcc, 0, v7, vcc
	global_load_dword v19, v[20:21], off
	v_add_co_u32_e32 v20, vcc, s28, v6
	v_lshl_add_u32 v5, v2, 12, v5
	s_nop 0
	v_addc_co_u32_e32 v21, vcc, 0, v7, vcc
	v_add_co_u32_e32 v22, vcc, s29, v6
	global_load_dword v20, v[20:21], off
	s_nop 0
	v_addc_co_u32_e32 v23, vcc, 0, v7, vcc
	global_load_dword v21, v[22:23], off
	v_add_co_u32_e32 v22, vcc, s30, v6
	v_sub_u32_e32 v5, v5, v49
	s_nop 0
	v_addc_co_u32_e32 v23, vcc, 0, v7, vcc
	v_add_co_u32_e32 v24, vcc, s31, v6
	global_load_dword v22, v[22:23], off
	s_nop 0
	v_addc_co_u32_e32 v25, vcc, 0, v7, vcc
	global_load_dword v23, v[24:25], off
	v_add_co_u32_e32 v24, vcc, s34, v6
	v_add_u32_e32 v51, v1, v5
	s_nop 0
	v_addc_co_u32_e32 v25, vcc, 0, v7, vcc
	v_add_co_u32_e32 v26, vcc, s35, v6
	global_load_dword v24, v[24:25], off
	s_nop 0
	v_addc_co_u32_e32 v27, vcc, 0, v7, vcc
	global_load_dword v25, v[26:27], off
	v_add_co_u32_e32 v26, vcc, s36, v6
	v_readlane_b32 s68, v250, 14
	s_nop 0
	v_addc_co_u32_e32 v27, vcc, 0, v7, vcc
	v_add_co_u32_e32 v28, vcc, s37, v6
	global_load_dword v26, v[26:27], off
	s_nop 0
	v_addc_co_u32_e32 v29, vcc, 0, v7, vcc
	global_load_dword v27, v[28:29], off
	v_add_co_u32_e32 v28, vcc, s38, v6
	v_readlane_b32 s69, v250, 15
	s_nop 0
	v_addc_co_u32_e32 v29, vcc, 0, v7, vcc
	v_add_co_u32_e32 v30, vcc, s39, v6
	global_load_dword v28, v[28:29], off
	s_nop 0
	v_addc_co_u32_e32 v31, vcc, 0, v7, vcc
	global_load_dword v29, v[30:31], off
	v_add_co_u32_e32 v30, vcc, s40, v6
	v_cmp_eq_u32_e64 s[0:1], 1, v2
	s_nop 0
	v_addc_co_u32_e32 v31, vcc, 0, v7, vcc
	v_add_co_u32_e32 v32, vcc, s41, v6
	global_load_dword v30, v[30:31], off
	s_nop 0
	v_addc_co_u32_e32 v33, vcc, 0, v7, vcc
	global_load_dword v31, v[32:33], off
	v_add_co_u32_e32 v32, vcc, s42, v6
	s_mov_b64 s[16:17], 0
	s_nop 0
	v_addc_co_u32_e32 v33, vcc, 0, v7, vcc
	v_add_co_u32_e32 v34, vcc, s43, v6
	global_load_dword v32, v[32:33], off
	s_nop 0
	v_addc_co_u32_e32 v35, vcc, 0, v7, vcc
	global_load_dword v33, v[34:35], off
	v_add_co_u32_e32 v34, vcc, s44, v6
	v_readlane_b32 s57, v250, 3
	s_nop 0
	v_addc_co_u32_e32 v35, vcc, 0, v7, vcc
	v_add_co_u32_e32 v36, vcc, s45, v6
	global_load_dword v34, v[34:35], off
	s_nop 0
	v_addc_co_u32_e32 v37, vcc, 0, v7, vcc
	global_load_dword v35, v[36:37], off
	v_add_co_u32_e32 v36, vcc, s46, v6
	v_readlane_b32 s58, v250, 4
	s_nop 0
	v_addc_co_u32_e32 v37, vcc, 0, v7, vcc
	v_add_co_u32_e32 v38, vcc, s47, v6
	global_load_dword v36, v[36:37], off
	s_nop 0
	v_addc_co_u32_e32 v39, vcc, 0, v7, vcc
	global_load_dword v37, v[38:39], off
	v_add_co_u32_e32 v38, vcc, s48, v6
	v_readlane_b32 s59, v250, 5
	s_nop 0
	v_addc_co_u32_e32 v39, vcc, 0, v7, vcc
	v_add_co_u32_e32 v40, vcc, s49, v6
	global_load_dword v38, v[38:39], off
	s_nop 0
	v_addc_co_u32_e32 v41, vcc, 0, v7, vcc
	global_load_dword v39, v[40:41], off
	v_add_co_u32_e32 v40, vcc, s50, v6
	v_readlane_b32 s60, v250, 6
	s_nop 0
	v_addc_co_u32_e32 v41, vcc, 0, v7, vcc
	v_add_co_u32_e32 v42, vcc, s51, v6
	global_load_dword v40, v[40:41], off
	s_nop 0
	v_addc_co_u32_e32 v43, vcc, 0, v7, vcc
	global_load_dword v41, v[42:43], off
	v_add_co_u32_e32 v42, vcc, s52, v6
	v_readlane_b32 s61, v250, 7
	s_nop 0
	v_addc_co_u32_e32 v43, vcc, 0, v7, vcc
	v_add_co_u32_e32 v44, vcc, s53, v6
	global_load_dword v42, v[42:43], off
	s_nop 0
	v_addc_co_u32_e32 v45, vcc, 0, v7, vcc
	global_load_dword v43, v[44:45], off
	v_add_co_u32_e32 v44, vcc, s54, v6
	v_readlane_b32 s62, v250, 8
	s_nop 0
	v_addc_co_u32_e32 v45, vcc, 0, v7, vcc
	v_add_co_u32_e32 v6, vcc, s55, v6
	global_load_dword v44, v[44:45], off
	s_nop 0
	v_addc_co_u32_e32 v7, vcc, 0, v7, vcc
	global_load_dword v45, v[6:7], off
	v_add_u32_e32 v6, 0x800, v51
	v_ashrrev_i32_e32 v7, 31, v6
	v_lshl_add_u64 v[6:7], v[6:7], 2, s[68:69]
	global_load_dword v46, v[6:7], off
	v_cmp_lt_i32_e32 vcc, 1, v2
	v_readlane_b32 s63, v250, 9
	v_readlane_b32 s64, v250, 10
	v_readlane_b32 s65, v250, 11
	v_readlane_b32 s70, v250, 16
	v_readlane_b32 s71, v250, 17
	s_and_saveexec_b64 s[14:15], vcc
	s_xor_b64 s[14:15], exec, s[14:15]
	s_cbranch_execz .LBB0_209
; __device__ __forceinline__ void p0b(Frame& F, const Args& AR) {
;     ...
;                 else if (l < DEPTH - 1) { vs = ng[((l + 1) * 6) * DM + c] * (1.0f + modval(l + 1, v, 1 * DM + c)); vh = modval(l + 1, v, c); } }
	s_mov_b32 s16, 0xd800
	v_cmp_gt_i32_e32 vcc, s16, v1
	s_mov_b64 s[18:19], 0
	v_mov_b32_e32 v2, 0
	s_and_saveexec_b64 s[16:17], vcc
	s_xor_b64 s[16:17], exec, s[16:17]
	s_cbranch_execz .LBB0_208
; __device__ __forceinline__ void p0b(Frame& F, const Args& AR) {
;     ...
;         auto modval = [&](int l, int v, int j) { float s = AR.in[I_BMOD][l * MODW + j]; const float* q = modp + (size_t)(l * 3 + v) * MODW + j;
;             for (int ch = 0; ch < MOD_CHUNKS; ++ch) s += q[(size_t)ch * DEPTH * 3 * MODW]; return s; };
;     ...
;                 else if (l < DEPTH - 1) { vs = ng[((l + 1) * 6) * DM + c] * (1.0f + modval(l + 1, v, 1 * DM + c)); vh = modval(l + 1, v, c); } }
	v_add_u32_e32 v5, 1, v50
	v_mul_i32_i24_e32 v2, 0x3000, v5
	v_sub_u32_e32 v2, v2, v49
	v_add_u32_e32 v6, v1, v2
	v_readlane_b32 s56, v250, 2
	v_ashrrev_i32_e32 v7, 31, v6
	v_readlane_b32 s68, v250, 14
	v_readlane_b32 s69, v250, 15
	v_readlane_b32 s66, v250, 12
	v_readlane_b32 s67, v250, 13
	v_lshl_add_u64 v[6:7], v[6:7], 2, s[68:69]
	global_load_dword v7, v[6:7], off
	v_mul_i32_i24_e32 v6, 0x4800, v5
	v_sub_u32_e32 v6, v6, v49
	v_add_u32_e32 v6, v1, v6
	v_add_u32_e32 v8, 0x800, v6
	v_ashrrev_i32_e32 v9, 31, v8
	v_lshl_add_u64 v[8:9], v[8:9], 2, s[66:67]
	global_load_dword v47, v[8:9], off
	v_mad_i32_i24 v5, v5, 3, v11
	v_mov_b64_e32 v[8:9], s[6:7]
	v_add_u32_e32 v2, 0x800, v4
	v_mad_i64_i32 v[8:9], s[18:19], v5, s22, v[8:9]
	v_lshl_add_u64 v[48:49], v[2:3], 2, v[8:9]
	v_add_co_u32_e32 v50, vcc, s23, v48
	global_load_dword v2, v[48:49], off
	s_nop 0
	v_addc_co_u32_e32 v51, vcc, 0, v49, vcc
	global_load_dword v5, v[50:51], off
	v_add_co_u32_e32 v50, vcc, s24, v48
	s_mov_b64 s[18:19], exec
	s_nop 0
	v_addc_co_u32_e32 v51, vcc, 0, v49, vcc
	v_readlane_b32 s57, v250, 3
	v_readlane_b32 s58, v250, 4
	v_readlane_b32 s59, v250, 5
	v_readlane_b32 s60, v250, 6
	v_readlane_b32 s61, v250, 7
	v_readlane_b32 s62, v250, 8
	v_readlane_b32 s63, v250, 9
	v_readlane_b32 s64, v250, 10
	v_readlane_b32 s65, v250, 11
	v_readlane_b32 s70, v250, 16
	v_readlane_b32 s71, v250, 17
	s_waitcnt vmcnt(1)
	v_add_f32_e32 v2, v47, v2
	s_waitcnt vmcnt(0)
	v_add_f32_e32 v2, v2, v5
	global_load_dword v100, v[50:51], off
	v_add_co_u32_e32 v50, vcc, s25, v48
	s_nop 1
	v_addc_co_u32_e32 v51, vcc, 0, v49, vcc
	global_load_dword v101, v[50:51], off
	v_add_co_u32_e32 v50, vcc, s26, v48
	s_nop 1
	v_addc_co_u32_e32 v51, vcc, 0, v49, vcc
	global_load_dword v102, v[50:51], off
	v_add_co_u32_e32 v50, vcc, s27, v48
	s_nop 1
	v_addc_co_u32_e32 v51, vcc, 0, v49, vcc
	global_load_dword v103, v[50:51], off
	v_add_co_u32_e32 v50, vcc, s28, v48
	s_nop 1
	v_addc_co_u32_e32 v51, vcc, 0, v49, vcc
	global_load_dword v104, v[50:51], off
	v_add_co_u32_e32 v50, vcc, s29, v48
	s_nop 1
	v_addc_co_u32_e32 v51, vcc, 0, v49, vcc
	global_load_dword v105, v[50:51], off
	v_add_co_u32_e32 v50, vcc, s30, v48
	s_nop 1
	v_addc_co_u32_e32 v51, vcc, 0, v49, vcc
	global_load_dword v106, v[50:51], off
	v_add_co_u32_e32 v50, vcc, s31, v48
	s_nop 1
	v_addc_co_u32_e32 v51, vcc, 0, v49, vcc
	global_load_dword v107, v[50:51], off
	v_add_co_u32_e32 v50, vcc, s34, v48
	s_nop 1
	v_addc_co_u32_e32 v51, vcc, 0, v49, vcc
	global_load_dword v108, v[50:51], off
	v_add_co_u32_e32 v50, vcc, s35, v48
	s_nop 1
	v_addc_co_u32_e32 v51, vcc, 0, v49, vcc
	global_load_dword v109, v[50:51], off
	v_add_co_u32_e32 v50, vcc, s36, v48
	s_nop 1
	v_addc_co_u32_e32 v51, vcc, 0, v49, vcc
	global_load_dword v110, v[50:51], off
	v_add_co_u32_e32 v50, vcc, s37, v48
	s_nop 1
	v_addc_co_u32_e32 v51, vcc, 0, v49, vcc
	global_load_dword v111, v[50:51], off
	v_add_co_u32_e32 v50, vcc, s38, v48
	s_nop 1
	v_addc_co_u32_e32 v51, vcc, 0, v49, vcc
	global_load_dword v112, v[50:51], off
	v_add_co_u32_e32 v50, vcc, s39, v48
	s_nop 1
	v_addc_co_u32_e32 v51, vcc, 0, v49, vcc
	global_load_dword v113, v[50:51], off
	v_add_co_u32_e32 v50, vcc, s40, v48
	s_nop 1
	v_addc_co_u32_e32 v51, vcc, 0, v49, vcc
	global_load_dword v114, v[50:51], off
	v_add_co_u32_e32 v50, vcc, s41, v48
	s_nop 1
	v_addc_co_u32_e32 v51, vcc, 0, v49, vcc
	global_load_dword v115, v[50:51], off
	v_add_co_u32_e32 v50, vcc, s42, v48
	s_nop 1
	v_addc_co_u32_e32 v51, vcc, 0, v49, vcc
	global_load_dword v116, v[50:51], off
	v_add_co_u32_e32 v50, vcc, s43, v48
	s_nop 1
	v_addc_co_u32_e32 v51, vcc, 0, v49, vcc
	global_load_dword v117, v[50:51], off
	v_add_co_u32_e32 v50, vcc, s44, v48
	s_nop 1
	v_addc_co_u32_e32 v51, vcc, 0, v49, vcc
	global_load_dword v118, v[50:51], off
	v_add_co_u32_e32 v50, vcc, s45, v48
	s_nop 1
	v_addc_co_u32_e32 v51, vcc, 0, v49, vcc
	global_load_dword v119, v[50:51], off
	v_add_co_u32_e32 v50, vcc, s46, v48
	s_nop 1
	v_addc_co_u32_e32 v51, vcc, 0, v49, vcc
	global_load_dword v120, v[50:51], off
	v_add_co_u32_e32 v50, vcc, s47, v48
	s_nop 1
	v_addc_co_u32_e32 v51, vcc, 0, v49, vcc
	global_load_dword v121, v[50:51], off
	v_add_co_u32_e32 v50, vcc, s48, v48
	s_nop 1
	v_addc_co_u32_e32 v51, vcc, 0, v49, vcc
	global_load_dword v122, v[50:51], off
	v_add_co_u32_e32 v50, vcc, s49, v48
	s_nop 1
	v_addc_co_u32_e32 v51, vcc, 0, v49, vcc
	global_load_dword v123, v[50:51], off
	v_add_co_u32_e32 v50, vcc, s50, v48
	s_nop 1
	v_addc_co_u32_e32 v51, vcc, 0, v49, vcc
	global_load_dword v124, v[50:51], off
	v_add_co_u32_e32 v50, vcc, s51, v48
	s_nop 1
	v_addc_co_u32_e32 v51, vcc, 0, v49, vcc
	global_load_dword v125, v[50:51], off
	v_add_co_u32_e32 v50, vcc, s52, v48
	s_nop 1
	v_addc_co_u32_e32 v51, vcc, 0, v49, vcc
	global_load_dword v126, v[50:51], off
	v_add_co_u32_e32 v50, vcc, s53, v48
	s_nop 1
	v_addc_co_u32_e32 v51, vcc, 0, v49, vcc
	global_load_dword v127, v[50:51], off
	v_add_co_u32_e32 v50, vcc, s54, v48
	s_nop 1
	v_addc_co_u32_e32 v51, vcc, 0, v49, vcc
	global_load_dword v128, v[50:51], off
	v_add_co_u32_e32 v48, vcc, s55, v48
	s_nop 1
	v_addc_co_u32_e32 v49, vcc, 0, v49, vcc
	s_waitcnt vmcnt(28)
	v_add_f32_e32 v2, v2, v100
	s_waitcnt vmcnt(27)
	v_add_f32_e32 v2, v2, v101
	s_waitcnt vmcnt(26)
	v_add_f32_e32 v2, v2, v102
	s_waitcnt vmcnt(25)
	v_add_f32_e32 v2, v2, v103
	s_waitcnt vmcnt(24)
	v_add_f32_e32 v2, v2, v104
	s_waitcnt vmcnt(23)
	v_add_f32_e32 v2, v2, v105
	s_waitcnt vmcnt(22)
	v_add_f32_e32 v2, v2, v106
	s_waitcnt vmcnt(21)
	v_add_f32_e32 v2, v2, v107
	s_waitcnt vmcnt(20)
	v_add_f32_e32 v2, v2, v108
	s_waitcnt vmcnt(19)
	v_add_f32_e32 v2, v2, v109
	s_waitcnt vmcnt(18)
	v_add_f32_e32 v2, v2, v110
	s_waitcnt vmcnt(17)
	v_add_f32_e32 v2, v2, v111
	s_waitcnt vmcnt(16)
	v_add_f32_e32 v2, v2, v112
	s_waitcnt vmcnt(15)
	v_add_f32_e32 v2, v2, v113
	s_waitcnt vmcnt(14)
	v_add_f32_e32 v2, v2, v114
	s_waitcnt vmcnt(13)
	v_add_f32_e32 v2, v2, v115
	s_waitcnt vmcnt(12)
	v_add_f32_e32 v2, v2, v116
	s_waitcnt vmcnt(11)
	v_add_f32_e32 v2, v2, v117
	s_waitcnt vmcnt(10)
	v_add_f32_e32 v2, v2, v118
	s_waitcnt vmcnt(9)
	v_add_f32_e32 v2, v2, v119
	s_waitcnt vmcnt(8)
	v_add_f32_e32 v2, v2, v120
	s_waitcnt vmcnt(7)
	v_add_f32_e32 v2, v2, v121
	s_waitcnt vmcnt(6)
	v_add_f32_e32 v2, v2, v122
	s_waitcnt vmcnt(5)
	v_add_f32_e32 v2, v2, v123
	s_waitcnt vmcnt(4)
	v_add_f32_e32 v2, v2, v124
	s_waitcnt vmcnt(3)
	v_add_f32_e32 v2, v2, v125
	s_waitcnt vmcnt(2)
	v_add_f32_e32 v2, v2, v126
	s_waitcnt vmcnt(1)
	v_add_f32_e32 v2, v2, v127
	s_waitcnt vmcnt(0)
	v_add_f32_e32 v2, v2, v128
	global_load_dword v5, v[48:49], off
	s_waitcnt vmcnt(0)
	v_add_f32_e32 v2, v2, v5
	v_add_f32_e32 v2, 1.0, v2
	v_mul_f32_e32 v2, v7, v2
	v_ashrrev_i32_e32 v7, 31, v6
	v_lshl_add_u64 v[6:7], v[6:7], 2, s[66:67]
	v_ashrrev_i32_e32 v5, 31, v4
	global_load_dword v47, v[6:7], off
	v_lshl_add_u64 v[6:7], v[4:5], 2, v[8:9]
	global_load_dword v5, v[6:7], off
	s_waitcnt vmcnt(0)
	v_add_f32_e32 v5, v47, v5

; __device__ __forceinline__ void p0b(Frame& F, const Args& AR) {
;     ...
;         auto modval = [&](int l, int v, int j) { float s = AR.in[I_BMOD][l * MODW + j]; const float* q = modp + (size_t)(l * 3 + v) * MODW + j;
;             for (int ch = 0; ch < MOD_CHUNKS; ++ch) s += q[(size_t)ch * DEPTH * 3 * MODW]; return s; };
;     ...
;                 if (k < 2) { vs = ng[(l * 6 + 2 + 2 * k) * DM + c] * (1.0f + modval(l, v, (4 + 3 * k) * DM + c)); vh = modval(l, v, (3 + 3 * k) * DM + c); }
.LBB0_209:
	s_andn2_saveexec_b64 s[14:15], s[14:15]
	s_cbranch_execz .LBB0_211
	v_add_u32_e32 v6, 0x1000, v51
	v_readlane_b32 s56, v250, 2
	v_ashrrev_i32_e32 v7, 31, v6
	v_readlane_b32 s68, v250, 14
	v_readlane_b32 s69, v250, 15
	v_add_u32_e32 v50, 0x2000, v48
	v_readlane_b32 s66, v250, 12
	v_lshl_add_u64 v[6:7], v[6:7], 2, s[68:69]
	global_load_dword v2, v[6:7], off
	v_add_u32_e32 v6, 0x2000, v47
	v_readlane_b32 s67, v250, 13
	v_ashrrev_i32_e32 v51, 31, v50
	v_ashrrev_i32_e32 v7, 31, v6
	v_lshl_add_u64 v[50:51], v[50:51], 2, s[66:67]
	v_lshl_add_u64 v[6:7], v[6:7], 2, v[8:9]
	global_load_dword v5, v[50:51], off
	global_load_dword v49, v[6:7], off
	v_add_co_u32_e32 v50, vcc, s23, v6
	v_add_u32_e32 v48, 0x1800, v48
	s_nop 0
	v_addc_co_u32_e32 v51, vcc, 0, v7, vcc
	s_or_b64 s[16:17], s[16:17], exec
	v_readlane_b32 s57, v250, 3
	v_readlane_b32 s58, v250, 4
	v_readlane_b32 s59, v250, 5
	v_readlane_b32 s60, v250, 6
	v_readlane_b32 s61, v250, 7
	v_readlane_b32 s62, v250, 8
	v_readlane_b32 s63, v250, 9
	v_readlane_b32 s64, v250, 10
	v_readlane_b32 s65, v250, 11
	v_readlane_b32 s70, v250, 16
	v_readlane_b32 s71, v250, 17
	s_waitcnt vmcnt(0)
	v_add_f32_e32 v5, v5, v49
	global_load_dword v100, v[50:51], off
	v_add_co_u32_e32 v50, vcc, s24, v6
	s_nop 1
	v_addc_co_u32_e32 v51, vcc, 0, v7, vcc
	global_load_dword v101, v[50:51], off
	v_add_co_u32_e32 v50, vcc, s25, v6
	s_nop 1
	v_addc_co_u32_e32 v51, vcc, 0, v7, vcc
	global_load_dword v102, v[50:51], off
	v_add_co_u32_e32 v50, vcc, s26, v6
	s_nop 1
	v_addc_co_u32_e32 v51, vcc, 0, v7, vcc
	global_load_dword v103, v[50:51], off
	v_add_co_u32_e32 v50, vcc, s27, v6
	s_nop 1
	v_addc_co_u32_e32 v51, vcc, 0, v7, vcc
	global_load_dword v104, v[50:51], off
	v_add_co_u32_e32 v50, vcc, s28, v6
	s_nop 1
	v_addc_co_u32_e32 v51, vcc, 0, v7, vcc
	global_load_dword v105, v[50:51], off
	v_add_co_u32_e32 v50, vcc, s29, v6
	s_nop 1
	v_addc_co_u32_e32 v51, vcc, 0, v7, vcc
	global_load_dword v106, v[50:51], off
	v_add_co_u32_e32 v50, vcc, s30, v6
	s_nop 1
	v_addc_co_u32_e32 v51, vcc, 0, v7, vcc
	global_load_dword v107, v[50:51], off
	v_add_co_u32_e32 v50, vcc, s31, v6
	s_nop 1
	v_addc_co_u32_e32 v51, vcc, 0, v7, vcc
	global_load_dword v108, v[50:51], off
	v_add_co_u32_e32 v50, vcc, s34, v6
	s_nop 1
	v_addc_co_u32_e32 v51, vcc, 0, v7, vcc
	global_load_dword v109, v[50:51], off
	v_add_co_u32_e32 v50, vcc, s35, v6
	s_nop 1
	v_addc_co_u32_e32 v51, vcc, 0, v7, vcc
	global_load_dword v110, v[50:51], off
	v_add_co_u32_e32 v50, vcc, s36, v6
	s_nop 1
	v_addc_co_u32_e32 v51, vcc, 0, v7, vcc
	global_load_dword v111, v[50:51], off
	v_add_co_u32_e32 v50, vcc, s37, v6
	s_nop 1
	v_addc_co_u32_e32 v51, vcc, 0, v7, vcc
	global_load_dword v112, v[50:51], off
	v_add_co_u32_e32 v50, vcc, s38, v6
	s_nop 1
	v_addc_co_u32_e32 v51, vcc, 0, v7, vcc
	global_load_dword v113, v[50:51], off
	v_add_co_u32_e32 v50, vcc, s39, v6
	s_nop 1
	v_addc_co_u32_e32 v51, vcc, 0, v7, vcc
	global_load_dword v114, v[50:51], off
	v_add_co_u32_e32 v50, vcc, s40, v6
	s_nop 1
	v_addc_co_u32_e32 v51, vcc, 0, v7, vcc
	global_load_dword v115, v[50:51], off
	v_add_co_u32_e32 v50, vcc, s41, v6
	s_nop 1
	v_addc_co_u32_e32 v51, vcc, 0, v7, vcc
	global_load_dword v116, v[50:51], off
	v_add_co_u32_e32 v50, vcc, s42, v6
	s_nop 1
	v_addc_co_u32_e32 v51, vcc, 0, v7, vcc
	global_load_dword v117, v[50:51], off
	v_add_co_u32_e32 v50, vcc, s43, v6
	s_nop 1
	v_addc_co_u32_e32 v51, vcc, 0, v7, vcc
	global_load_dword v118, v[50:51], off
	v_add_co_u32_e32 v50, vcc, s44, v6
	s_nop 1
	v_addc_co_u32_e32 v51, vcc, 0, v7, vcc
	global_load_dword v119, v[50:51], off
	v_add_co_u32_e32 v50, vcc, s45, v6
	s_nop 1
	v_addc_co_u32_e32 v51, vcc, 0, v7, vcc
	global_load_dword v120, v[50:51], off
	v_add_co_u32_e32 v50, vcc, s46, v6
	s_nop 1
	v_addc_co_u32_e32 v51, vcc, 0, v7, vcc
	global_load_dword v121, v[50:51], off
	v_add_co_u32_e32 v50, vcc, s47, v6
	s_nop 1
	v_addc_co_u32_e32 v51, vcc, 0, v7, vcc
	global_load_dword v122, v[50:51], off
	v_add_co_u32_e32 v50, vcc, s48, v6
	s_nop 1
	v_addc_co_u32_e32 v51, vcc, 0, v7, vcc
	global_load_dword v123, v[50:51], off
	v_add_co_u32_e32 v50, vcc, s49, v6
	s_nop 1
	v_addc_co_u32_e32 v51, vcc, 0, v7, vcc
	global_load_dword v124, v[50:51], off
	v_add_co_u32_e32 v50, vcc, s50, v6
	s_nop 1
	v_addc_co_u32_e32 v51, vcc, 0, v7, vcc
	global_load_dword v125, v[50:51], off
	v_add_co_u32_e32 v50, vcc, s51, v6
	s_nop 1
	v_addc_co_u32_e32 v51, vcc, 0, v7, vcc
	global_load_dword v126, v[50:51], off
	v_add_co_u32_e32 v50, vcc, s52, v6
	s_nop 1
	v_addc_co_u32_e32 v51, vcc, 0, v7, vcc
	global_load_dword v127, v[50:51], off
	v_add_co_u32_e32 v50, vcc, s53, v6
	s_nop 1
	v_addc_co_u32_e32 v51, vcc, 0, v7, vcc
	global_load_dword v128, v[50:51], off
	v_add_co_u32_e32 v50, vcc, s54, v6
	s_nop 1
	v_addc_co_u32_e32 v51, vcc, 0, v7, vcc
	s_waitcnt vmcnt(28)
	v_add_f32_e32 v5, v5, v100
	s_waitcnt vmcnt(27)
	v_add_f32_e32 v5, v5, v101
	s_waitcnt vmcnt(26)
	v_add_f32_e32 v5, v5, v102
	s_waitcnt vmcnt(25)
	v_add_f32_e32 v5, v5, v103
	s_waitcnt vmcnt(24)
	v_add_f32_e32 v5, v5, v104
	s_waitcnt vmcnt(23)
	v_add_f32_e32 v5, v5, v105
	s_waitcnt vmcnt(22)
	v_add_f32_e32 v5, v5, v106
	s_waitcnt vmcnt(21)
	v_add_f32_e32 v5, v5, v107
	s_waitcnt vmcnt(20)
	v_add_f32_e32 v5, v5, v108
	s_waitcnt vmcnt(19)
	v_add_f32_e32 v5, v5, v109
	s_waitcnt vmcnt(18)
	v_add_f32_e32 v5, v5, v110
	s_waitcnt vmcnt(17)
	v_add_f32_e32 v5, v5, v111
	s_waitcnt vmcnt(16)
	v_add_f32_e32 v5, v5, v112
	s_waitcnt vmcnt(15)
	v_add_f32_e32 v5, v5, v113
	s_waitcnt vmcnt(14)
	v_add_f32_e32 v5, v5, v114
	s_waitcnt vmcnt(13)
	v_add_f32_e32 v5, v5, v115
	s_waitcnt vmcnt(12)
	v_add_f32_e32 v5, v5, v116
	s_waitcnt vmcnt(11)
	v_add_f32_e32 v5, v5, v117
	s_waitcnt vmcnt(10)
	v_add_f32_e32 v5, v5, v118
	s_waitcnt vmcnt(9)
	v_add_f32_e32 v5, v5, v119
	s_waitcnt vmcnt(8)
	v_add_f32_e32 v5, v5, v120
	s_waitcnt vmcnt(7)
	v_add_f32_e32 v5, v5, v121
	s_waitcnt vmcnt(6)
	v_add_f32_e32 v5, v5, v122
	s_waitcnt vmcnt(5)
	v_add_f32_e32 v5, v5, v123
	s_waitcnt vmcnt(4)
	v_add_f32_e32 v5, v5, v124
	s_waitcnt vmcnt(3)
	v_add_f32_e32 v5, v5, v125
	s_waitcnt vmcnt(2)
	v_add_f32_e32 v5, v5, v126
	s_waitcnt vmcnt(1)
	v_add_f32_e32 v5, v5, v127
	s_waitcnt vmcnt(0)
	v_add_f32_e32 v5, v5, v128
	v_add_co_u32_e32 v6, vcc, s55, v6
	global_load_dword v49, v[50:51], off
	s_nop 0
	v_addc_co_u32_e32 v7, vcc, 0, v7, vcc
	global_load_dword v6, v[6:7], off
	s_waitcnt vmcnt(1)
	v_add_f32_e32 v5, v5, v49
	v_ashrrev_i32_e32 v49, 31, v48
	v_lshl_add_u64 v[48:49], v[48:49], 2, s[66:67]
	s_waitcnt vmcnt(0)
	v_add_f32_e32 v5, v5, v6
	v_add_u32_e32 v6, 0x1800, v47
	v_ashrrev_i32_e32 v7, 31, v6
	v_add_f32_e32 v5, 1.0, v5
	v_lshl_add_u64 v[6:7], v[6:7], 2, v[8:9]
	v_mul_f32_e32 v2, v2, v5
	global_load_dword v5, v[48:49], off
	global_load_dword v8, v[6:7], off
	s_waitcnt vmcnt(0)
	v_add_f32_e32 v5, v5, v8

; __device__ __forceinline__ void p0b(Frame& F, const Args& AR) {
;     ...
;         auto modval = [&](int l, int v, int j) { float s = AR.in[I_BMOD][l * MODW + j]; const float* q = modp + (size_t)(l * 3 + v) * MODW + j;
;             for (int ch = 0; ch < MOD_CHUNKS; ++ch) s += q[(size_t)ch * DEPTH * 3 * MODW]; return s; };
;         for (int e = gt; e < 13 * 3 * DM; e += NGT) { const int c = e % DM, v = (e / DM) % 3, idx = e / (3 * DM);
;             float vg = 0.f, vs = 0.f, vh = 0.f;
;             if (idx == 12) { vs = ng[c] * (1.0f + modval(0, v, 1 * DM + c)); vh = modval(0, v, c); }
.LBB0_214:
	v_mov_b32_e32 v5, v3
	v_readlane_b32 s56, v250, 2
	v_lshlrev_b64 v[6:7], 2, v[4:5]
	v_readlane_b32 s68, v250, 14
	v_readlane_b32 s69, v250, 15
	v_add_u32_e32 v2, 0x800, v4
	v_readlane_b32 s66, v250, 12
	v_readlane_b32 s67, v250, 13
	v_lshl_add_u64 v[8:9], s[68:69], 0, v[6:7]
	v_lshlrev_b64 v[12:13], 2, v[2:3]
	global_load_dword v5, v[8:9], off
	v_lshl_add_u64 v[8:9], s[66:67], 0, v[12:13]
	v_mul_i32_i24_e32 v2, 0x12000, v11
	global_load_dword v15, v[8:9], off
	v_lshl_add_u64 v[8:9], s[6:7], 0, v[2:3]
	v_lshl_add_u64 v[12:13], v[8:9], 0, v[12:13]
	global_load_dword v2, v[12:13], off
	v_add_co_u32_e32 v16, vcc, 0xd8000, v12
	v_readlane_b32 s57, v250, 3
	s_nop 0
	v_addc_co_u32_e32 v17, vcc, 0, v13, vcc
	v_readlane_b32 s58, v250, 4
	v_readlane_b32 s59, v250, 5
	v_readlane_b32 s60, v250, 6
	v_readlane_b32 s61, v250, 7
	v_readlane_b32 s62, v250, 8
	v_readlane_b32 s63, v250, 9
	v_readlane_b32 s64, v250, 10
	v_readlane_b32 s65, v250, 11
	v_readlane_b32 s70, v250, 16
	v_readlane_b32 s71, v250, 17
	s_or_b64 s[0:1], s[0:1], exec
	s_waitcnt vmcnt(0)
	v_add_f32_e32 v2, v15, v2
	global_load_dword v100, v[16:17], off
	v_add_co_u32_e32 v16, vcc, 0x1b0000, v12
	s_nop 1
	v_addc_co_u32_e32 v17, vcc, 0, v13, vcc
	global_load_dword v101, v[16:17], off
	v_add_co_u32_e32 v16, vcc, 0x288000, v12
	s_nop 1
	v_addc_co_u32_e32 v17, vcc, 0, v13, vcc
	global_load_dword v102, v[16:17], off
	v_add_co_u32_e32 v16, vcc, 0x360000, v12
	s_nop 1
	v_addc_co_u32_e32 v17, vcc, 0, v13, vcc
	global_load_dword v103, v[16:17], off
	v_add_co_u32_e32 v16, vcc, 0x438000, v12
	s_nop 1
	v_addc_co_u32_e32 v17, vcc, 0, v13, vcc
	global_load_dword v104, v[16:17], off
	v_add_co_u32_e32 v16, vcc, 0x510000, v12
	s_nop 1
	v_addc_co_u32_e32 v17, vcc, 0, v13, vcc
	global_load_dword v105, v[16:17], off
	v_add_co_u32_e32 v16, vcc, 0x5e8000, v12
	s_nop 1
	v_addc_co_u32_e32 v17, vcc, 0, v13, vcc
	global_load_dword v106, v[16:17], off
	v_add_co_u32_e32 v16, vcc, 0x6c0000, v12
	s_nop 1
	v_addc_co_u32_e32 v17, vcc, 0, v13, vcc
	global_load_dword v107, v[16:17], off
	v_add_co_u32_e32 v16, vcc, 0x798000, v12
	s_nop 1
	v_addc_co_u32_e32 v17, vcc, 0, v13, vcc
	global_load_dword v108, v[16:17], off
	v_add_co_u32_e32 v16, vcc, 0x870000, v12
	s_nop 1
	v_addc_co_u32_e32 v17, vcc, 0, v13, vcc
	global_load_dword v109, v[16:17], off
	v_add_co_u32_e32 v16, vcc, 0x948000, v12
	s_nop 1
	v_addc_co_u32_e32 v17, vcc, 0, v13, vcc
	global_load_dword v110, v[16:17], off
	v_add_co_u32_e32 v16, vcc, 0xa20000, v12
	s_nop 1
	v_addc_co_u32_e32 v17, vcc, 0, v13, vcc
	global_load_dword v111, v[16:17], off
	v_add_co_u32_e32 v16, vcc, 0xaf8000, v12
	s_nop 1
	v_addc_co_u32_e32 v17, vcc, 0, v13, vcc
	global_load_dword v112, v[16:17], off
	v_add_co_u32_e32 v16, vcc, 0xbd0000, v12
	s_nop 1
	v_addc_co_u32_e32 v17, vcc, 0, v13, vcc
	global_load_dword v113, v[16:17], off
	v_add_co_u32_e32 v16, vcc, 0xca8000, v12
	s_nop 1
	v_addc_co_u32_e32 v17, vcc, 0, v13, vcc
	global_load_dword v114, v[16:17], off
	v_add_co_u32_e32 v16, vcc, 0xd80000, v12
	s_nop 1
	v_addc_co_u32_e32 v17, vcc, 0, v13, vcc
	global_load_dword v115, v[16:17], off
	v_add_co_u32_e32 v16, vcc, 0xe58000, v12
	s_nop 1
	v_addc_co_u32_e32 v17, vcc, 0, v13, vcc
	global_load_dword v116, v[16:17], off
	v_add_co_u32_e32 v16, vcc, 0xf30000, v12
	s_nop 1
	v_addc_co_u32_e32 v17, vcc, 0, v13, vcc
	global_load_dword v117, v[16:17], off
	v_add_co_u32_e32 v16, vcc, 0x1008000, v12
	s_nop 1
	v_addc_co_u32_e32 v17, vcc, 0, v13, vcc
	global_load_dword v118, v[16:17], off
	v_add_co_u32_e32 v16, vcc, 0x10e0000, v12
	s_nop 1
	v_addc_co_u32_e32 v17, vcc, 0, v13, vcc
	global_load_dword v119, v[16:17], off
	v_add_co_u32_e32 v16, vcc, 0x11b8000, v12
	s_nop 1
	v_addc_co_u32_e32 v17, vcc, 0, v13, vcc
	global_load_dword v120, v[16:17], off
	v_add_co_u32_e32 v16, vcc, 0x1290000, v12
	s_nop 1
	v_addc_co_u32_e32 v17, vcc, 0, v13, vcc
	global_load_dword v121, v[16:17], off
	v_add_co_u32_e32 v16, vcc, 0x1368000, v12
	s_nop 1
	v_addc_co_u32_e32 v17, vcc, 0, v13, vcc
	global_load_dword v122, v[16:17], off
	v_add_co_u32_e32 v16, vcc, 0x1440000, v12
	s_nop 1
	v_addc_co_u32_e32 v17, vcc, 0, v13, vcc
	global_load_dword v123, v[16:17], off
	v_add_co_u32_e32 v16, vcc, 0x1518000, v12
	s_nop 1
	v_addc_co_u32_e32 v17, vcc, 0, v13, vcc
	global_load_dword v124, v[16:17], off
	v_add_co_u32_e32 v16, vcc, 0x15f0000, v12
	s_nop 1
	v_addc_co_u32_e32 v17, vcc, 0, v13, vcc
	global_load_dword v125, v[16:17], off
	v_add_co_u32_e32 v16, vcc, 0x16c8000, v12
	s_nop 1
	v_addc_co_u32_e32 v17, vcc, 0, v13, vcc
	global_load_dword v126, v[16:17], off
	v_add_co_u32_e32 v16, vcc, 0x17a0000, v12
	s_nop 1
	v_addc_co_u32_e32 v17, vcc, 0, v13, vcc
	global_load_dword v127, v[16:17], off
	v_add_co_u32_e32 v16, vcc, 0x1878000, v12
	s_nop 1
	v_addc_co_u32_e32 v17, vcc, 0, v13, vcc
	global_load_dword v128, v[16:17], off
	v_add_co_u32_e32 v16, vcc, 0x1950000, v12
	s_nop 1
	v_addc_co_u32_e32 v17, vcc, 0, v13, vcc
	s_waitcnt vmcnt(28)
	v_add_f32_e32 v2, v2, v100
	s_waitcnt vmcnt(27)
	v_add_f32_e32 v2, v2, v101
	s_waitcnt vmcnt(26)
	v_add_f32_e32 v2, v2, v102
	s_waitcnt vmcnt(25)
	v_add_f32_e32 v2, v2, v103
	s_waitcnt vmcnt(24)
	v_add_f32_e32 v2, v2, v104
	s_waitcnt vmcnt(23)
	v_add_f32_e32 v2, v2, v105
	s_waitcnt vmcnt(22)
	v_add_f32_e32 v2, v2, v106
	s_waitcnt vmcnt(21)
	v_add_f32_e32 v2, v2, v107
	s_waitcnt vmcnt(20)
	v_add_f32_e32 v2, v2, v108
	s_waitcnt vmcnt(19)
	v_add_f32_e32 v2, v2, v109
	s_waitcnt vmcnt(18)
	v_add_f32_e32 v2, v2, v110
	s_waitcnt vmcnt(17)
	v_add_f32_e32 v2, v2, v111
	s_waitcnt vmcnt(16)
	v_add_f32_e32 v2, v2, v112
	s_waitcnt vmcnt(15)
	v_add_f32_e32 v2, v2, v113
	s_waitcnt vmcnt(14)
	v_add_f32_e32 v2, v2, v114
	s_waitcnt vmcnt(13)
; __device__ __forceinline__ void p0b(Frame& F, const Args& AR) {
;     ...
;         auto modval = [&](int l, int v, int j) { float s = AR.in[I_BMOD][l * MODW + j]; const float* q = modp + (size_t)(l * 3 + v) * MODW + j;
;             for (int ch = 0; ch < MOD_CHUNKS; ++ch) s += q[(size_t)ch * DEPTH * 3 * MODW]; return s; };
;         for (int e = gt; e < 13 * 3 * DM; e += NGT) { const int c = e % DM, v = (e / DM) % 3, idx = e / (3 * DM);
;             float vg = 0.f, vs = 0.f, vh = 0.f;
;             if (idx == 12) { vs = ng[c] * (1.0f + modval(0, v, 1 * DM + c)); vh = modval(0, v, c); }
	v_add_f32_e32 v2, v2, v115
	s_waitcnt vmcnt(12)
	v_add_f32_e32 v2, v2, v116
	s_waitcnt vmcnt(11)
	v_add_f32_e32 v2, v2, v117
	s_waitcnt vmcnt(10)
	v_add_f32_e32 v2, v2, v118
	s_waitcnt vmcnt(9)
	v_add_f32_e32 v2, v2, v119
	s_waitcnt vmcnt(8)
	v_add_f32_e32 v2, v2, v120
	s_waitcnt vmcnt(7)
	v_add_f32_e32 v2, v2, v121
	s_waitcnt vmcnt(6)
	v_add_f32_e32 v2, v2, v122
	s_waitcnt vmcnt(5)
	v_add_f32_e32 v2, v2, v123
	s_waitcnt vmcnt(4)
	v_add_f32_e32 v2, v2, v124
	s_waitcnt vmcnt(3)
	v_add_f32_e32 v2, v2, v125
	s_waitcnt vmcnt(2)
	v_add_f32_e32 v2, v2, v126
	s_waitcnt vmcnt(1)
	v_add_f32_e32 v2, v2, v127
	s_waitcnt vmcnt(0)
	v_add_f32_e32 v2, v2, v128
	v_add_co_u32_e32 v12, vcc, 0x1a28000, v12
	global_load_dword v15, v[16:17], off
	s_nop 0
	v_addc_co_u32_e32 v13, vcc, 0, v13, vcc
	global_load_dword v12, v[12:13], off
	s_waitcnt vmcnt(1)
	v_add_f32_e32 v2, v2, v15
	s_waitcnt vmcnt(0)
	v_add_f32_e32 v2, v2, v12
	v_add_f32_e32 v2, 1.0, v2
	v_lshl_add_u64 v[12:13], s[66:67], 0, v[6:7]
	v_lshl_add_u64 v[6:7], v[8:9], 0, v[6:7]
	v_mul_f32_e32 v2, v5, v2
	global_load_dword v5, v[12:13], off
	global_load_dword v8, v[6:7], off
	v_readlane_b32 s56, v250, 34
	v_readlane_b32 s58, v250, 36
	v_readlane_b32 s59, v250, 37
	v_readlane_b32 s60, v250, 38
	v_readlane_b32 s61, v250, 39
	v_readlane_b32 s62, v250, 40
	v_readlane_b32 s63, v250, 41
	v_readlane_b32 s57, v250, 35
	v_readlane_b32 s64, v250, 42
	v_readlane_b32 s65, v250, 43
	v_readlane_b32 s66, v250, 44
	v_readlane_b32 s67, v250, 45
	v_readlane_b32 s68, v250, 46
	v_readlane_b32 s69, v250, 47
	v_readlane_b32 s70, v250, 48
	v_readlane_b32 s71, v250, 49
	s_waitcnt vmcnt(0)
	v_add_f32_e32 v5, v5, v8
	v_mov_b32_e32 v8, 0
	s_or_b64 exec, exec, s[12:13]
	v_mov_b32_e32 v9, 0
	s_and_saveexec_b64 s[12:13], s[0:1]
	s_cbranch_execz .LBB0_203
; __device__ __forceinline__ void p0b(Frame& F, const Args& AR) {
;     ...
;         auto modval = [&](int l, int v, int j) { float s = AR.in[I_BMOD][l * MODW + j]; const float* q = modp + (size_t)(l * 3 + v) * MODW + j;
;             for (int ch = 0; ch < MOD_CHUNKS; ++ch) s += q[(size_t)ch * DEPTH * 3 * MODW]; return s; };
;         for (int e = gt; e < 13 * 3 * DM; e += NGT) { const int c = e % DM, v = (e / DM) % 3, idx = e / (3 * DM);
;             float vg = 0.f, vs = 0.f, vh = 0.f;
;             if (idx == 12) { vs = ng[c] * (1.0f + modval(0, v, 1 * DM + c)); vh = modval(0, v, c); }
.LBB0_215:
	v_add_co_u32_e32 v12, vcc, 0xd8000, v6
	s_nop 1
	v_addc_co_u32_e32 v13, vcc, 0, v7, vcc
	global_load_dword v100, v[12:13], off
	v_add_co_u32_e32 v12, vcc, 0x1b0000, v6
	s_nop 1
	v_addc_co_u32_e32 v13, vcc, 0, v7, vcc
	global_load_dword v101, v[12:13], off
	v_add_co_u32_e32 v12, vcc, 0x288000, v6
	s_nop 1
	v_addc_co_u32_e32 v13, vcc, 0, v7, vcc
	global_load_dword v102, v[12:13], off
	v_add_co_u32_e32 v12, vcc, 0x360000, v6
	s_nop 1
	v_addc_co_u32_e32 v13, vcc, 0, v7, vcc
	global_load_dword v103, v[12:13], off
	v_add_co_u32_e32 v12, vcc, 0x438000, v6
	s_nop 1
	v_addc_co_u32_e32 v13, vcc, 0, v7, vcc
	global_load_dword v104, v[12:13], off
	v_add_co_u32_e32 v12, vcc, 0x510000, v6
	s_nop 1
	v_addc_co_u32_e32 v13, vcc, 0, v7, vcc
	global_load_dword v105, v[12:13], off
	v_add_co_u32_e32 v12, vcc, 0x5e8000, v6
	s_nop 1
	v_addc_co_u32_e32 v13, vcc, 0, v7, vcc
	global_load_dword v106, v[12:13], off
	v_add_co_u32_e32 v12, vcc, 0x6c0000, v6
	s_nop 1
	v_addc_co_u32_e32 v13, vcc, 0, v7, vcc
	global_load_dword v107, v[12:13], off
	v_add_co_u32_e32 v12, vcc, 0x798000, v6
	s_nop 1
	v_addc_co_u32_e32 v13, vcc, 0, v7, vcc
	global_load_dword v108, v[12:13], off
	v_add_co_u32_e32 v12, vcc, 0x870000, v6
	s_nop 1
	v_addc_co_u32_e32 v13, vcc, 0, v7, vcc
	global_load_dword v109, v[12:13], off
	v_add_co_u32_e32 v12, vcc, 0x948000, v6
	s_nop 1
	v_addc_co_u32_e32 v13, vcc, 0, v7, vcc
	global_load_dword v110, v[12:13], off
	v_add_co_u32_e32 v12, vcc, 0xa20000, v6
	s_nop 1
	v_addc_co_u32_e32 v13, vcc, 0, v7, vcc
	global_load_dword v111, v[12:13], off
	v_add_co_u32_e32 v12, vcc, 0xaf8000, v6
	s_nop 1
	v_addc_co_u32_e32 v13, vcc, 0, v7, vcc
	global_load_dword v112, v[12:13], off
	v_add_co_u32_e32 v12, vcc, 0xbd0000, v6
	s_nop 1
	v_addc_co_u32_e32 v13, vcc, 0, v7, vcc
	global_load_dword v113, v[12:13], off
	v_add_co_u32_e32 v12, vcc, 0xca8000, v6
	s_nop 1
	v_addc_co_u32_e32 v13, vcc, 0, v7, vcc
	global_load_dword v114, v[12:13], off
	v_add_co_u32_e32 v12, vcc, 0xd80000, v6
	s_nop 1
	v_addc_co_u32_e32 v13, vcc, 0, v7, vcc
	global_load_dword v115, v[12:13], off
	v_add_co_u32_e32 v12, vcc, 0xe58000, v6
	s_nop 1
	v_addc_co_u32_e32 v13, vcc, 0, v7, vcc
	global_load_dword v116, v[12:13], off
	v_add_co_u32_e32 v12, vcc, 0xf30000, v6
	s_nop 1
	v_addc_co_u32_e32 v13, vcc, 0, v7, vcc
	global_load_dword v117, v[12:13], off
	v_add_co_u32_e32 v12, vcc, 0x1008000, v6
	s_nop 1
	v_addc_co_u32_e32 v13, vcc, 0, v7, vcc
	global_load_dword v118, v[12:13], off
	v_add_co_u32_e32 v12, vcc, 0x10e0000, v6
	s_nop 1
	v_addc_co_u32_e32 v13, vcc, 0, v7, vcc
	global_load_dword v119, v[12:13], off
	v_add_co_u32_e32 v12, vcc, 0x11b8000, v6
	s_nop 1
	v_addc_co_u32_e32 v13, vcc, 0, v7, vcc
	global_load_dword v120, v[12:13], off
	v_add_co_u32_e32 v12, vcc, 0x1290000, v6
	s_nop 1
	v_addc_co_u32_e32 v13, vcc, 0, v7, vcc
	global_load_dword v121, v[12:13], off
	v_add_co_u32_e32 v12, vcc, 0x1368000, v6
	s_nop 1
	v_addc_co_u32_e32 v13, vcc, 0, v7, vcc
	global_load_dword v122, v[12:13], off
	v_add_co_u32_e32 v12, vcc, 0x1440000, v6
	s_nop 1
	v_addc_co_u32_e32 v13, vcc, 0, v7, vcc
	global_load_dword v123, v[12:13], off
	v_add_co_u32_e32 v12, vcc, 0x1518000, v6
	s_nop 1
	v_addc_co_u32_e32 v13, vcc, 0, v7, vcc
	global_load_dword v124, v[12:13], off
	v_add_co_u32_e32 v12, vcc, 0x15f0000, v6
	s_nop 1
	v_addc_co_u32_e32 v13, vcc, 0, v7, vcc
	global_load_dword v125, v[12:13], off
	v_add_co_u32_e32 v12, vcc, 0x16c8000, v6
	s_nop 1
	v_addc_co_u32_e32 v13, vcc, 0, v7, vcc
	global_load_dword v126, v[12:13], off
	v_add_co_u32_e32 v12, vcc, 0x17a0000, v6
	s_nop 1
	v_addc_co_u32_e32 v13, vcc, 0, v7, vcc
	global_load_dword v127, v[12:13], off
	v_add_co_u32_e32 v12, vcc, 0x1878000, v6
	s_nop 1
	v_addc_co_u32_e32 v13, vcc, 0, v7, vcc
	global_load_dword v128, v[12:13], off
	v_add_co_u32_e32 v12, vcc, 0x1950000, v6
	s_nop 1
	v_addc_co_u32_e32 v13, vcc, 0, v7, vcc
	s_waitcnt vmcnt(28)
	v_add_f32_e32 v5, v5, v100
	s_waitcnt vmcnt(27)
	v_add_f32_e32 v5, v5, v101
	s_waitcnt vmcnt(26)
	v_add_f32_e32 v5, v5, v102
	s_waitcnt vmcnt(25)
	v_add_f32_e32 v5, v5, v103
	s_waitcnt vmcnt(24)
	v_add_f32_e32 v5, v5, v104
	s_waitcnt vmcnt(23)
	v_add_f32_e32 v5, v5, v105
	s_waitcnt vmcnt(22)
	v_add_f32_e32 v5, v5, v106
	s_waitcnt vmcnt(21)
	v_add_f32_e32 v5, v5, v107
	s_waitcnt vmcnt(20)
	v_add_f32_e32 v5, v5, v108
	s_waitcnt vmcnt(19)
	v_add_f32_e32 v5, v5, v109
	s_waitcnt vmcnt(18)
	v_add_f32_e32 v5, v5, v110
	s_waitcnt vmcnt(17)
	v_add_f32_e32 v5, v5, v111
	s_waitcnt vmcnt(16)
	v_add_f32_e32 v5, v5, v112
	s_waitcnt vmcnt(15)
	v_add_f32_e32 v5, v5, v113
	s_waitcnt vmcnt(14)
	v_add_f32_e32 v5, v5, v114
	s_waitcnt vmcnt(13)
	v_add_f32_e32 v5, v5, v115
	s_waitcnt vmcnt(12)
	v_add_f32_e32 v5, v5, v116
	s_waitcnt vmcnt(11)
	v_add_f32_e32 v5, v5, v117
	s_waitcnt vmcnt(10)
	v_add_f32_e32 v5, v5, v118
	s_waitcnt vmcnt(9)
	v_add_f32_e32 v5, v5, v119
	s_waitcnt vmcnt(8)
	v_add_f32_e32 v5, v5, v120
	s_waitcnt vmcnt(7)
	v_add_f32_e32 v5, v5, v121
	s_waitcnt vmcnt(6)
	v_add_f32_e32 v5, v5, v122
	s_waitcnt vmcnt(5)
	v_add_f32_e32 v5, v5, v123
	s_waitcnt vmcnt(4)
	v_add_f32_e32 v5, v5, v124
	s_waitcnt vmcnt(3)
	v_add_f32_e32 v5, v5, v125
	s_waitcnt vmcnt(2)
	v_add_f32_e32 v5, v5, v126
	s_waitcnt vmcnt(1)
	v_add_f32_e32 v5, v5, v127
	s_waitcnt vmcnt(0)
	v_add_f32_e32 v5, v5, v128
	v_add_co_u32_e32 v6, vcc, 0x1a28000, v6
	global_load_dword v9, v[12:13], off
	s_nop 0
	v_addc_co_u32_e32 v7, vcc, 0, v7, vcc
	global_load_dword v6, v[6:7], off
	s_waitcnt vmcnt(1)
	v_add_f32_e32 v5, v5, v9
	s_waitcnt vmcnt(0)
	v_add_f32_e32 v9, v5, v6
	s_branch .LBB0_203
